# mix phase: static item assignment computed on the scalar unit instead of the ticket queues (no fetch-add round trip / LDS broadcast / second barrier per item)
# speedup vs baseline: 1.0167x; 1.0167x over previous
.LBB0_112:
	s_andn2_b64 vcc, exec, s[0:1]
	s_cbranch_vccnz .LBB0_166
	v_readlane_b32 s0, v214, 57
	v_readlane_b32 s1, v214, 58
	s_mov_b32 s40, s0
	s_lshl_b32 s0, s0, 7
	s_ashr_i32 s1, s0, 31
	s_lshl_b64 s[0:1], s[0:1], 2
	v_readlane_b32 s2, v217, 32
	s_add_u32 s38, s2, s0
	v_readlane_b32 s0, v217, 33
	s_addc_u32 s39, s0, s1
	v_readlane_b32 s0, v214, 34
	s_add_u32 s0, s38, s0
	v_cvt_f32_i32_e32 v0, s40
	s_addc_u32 s1, s39, 0
	v_writelane_b32 v214, s0, 61
	s_ashr_i32 s41, s40, 31
	v_mul_f32_e32 v0, 0xbe99999a, v0
	v_writelane_b32 v214, s1, 62
	s_lshl_b32 s20, s40, 2
	v_readlane_b32 s4, v214, 40
	s_lshl_b64 s[0:1], s[40:41], 12
	v_readlane_b32 s12, v214, 48
	v_mul_f32_e32 v0, 0x3fb8aa3b, v0
	v_readlane_b32 s13, v214, 49
	s_add_u32 s86, s12, s0
	v_exp_f32_e32 v0, v0
	v_readlane_b32 s18, v214, 54
	s_addc_u32 s87, s13, s1
	s_lshl_b64 s[0:1], s[40:41], 10
	v_readlane_b32 s5, v214, 41
	v_readlane_b32 s6, v214, 42
	v_readlane_b32 s7, v214, 43
	v_readlane_b32 s8, v214, 44
	v_readlane_b32 s9, v214, 45
	v_readlane_b32 s10, v214, 46
	v_readlane_b32 s11, v214, 47
	v_readlane_b32 s14, v214, 50
	v_readlane_b32 s15, v214, 51
	v_readlane_b32 s16, v214, 52
	v_readlane_b32 s17, v214, 53
	v_readlane_b32 s19, v214, 55
	s_add_u32 s42, s18, s0
	s_addc_u32 s43, s19, s1
	s_lshl_b64 s[0:1], s[40:41], 9
	v_readlane_b32 s4, v217, 50
	v_fmamk_f32 v116, v0, 0xbf19999a, v145
	v_readlane_b32 s5, v217, 51
	v_readlane_b32 s19, v216, 1
	s_add_u32 s92, s4, s0
	s_mov_b32 s0, s40
	v_sub_f32_e32 v119, 1.0, v116
	s_addc_u32 s93, s5, s1
	s_lshl_b32 s19, s40, 1
	v_writelane_b32 v214, s0, 57
	s_lshl_b32 s94, s40, 4
	s_mov_b64 s[96:97], 0
	s_mov_b64 s[2:3], 0
	v_readlane_b32 s6, v217, 52
	v_readlane_b32 s7, v217, 53
	v_readlane_b32 s8, v217, 54
	v_readlane_b32 s9, v217, 55
	v_readlane_b32 s10, v217, 56
	v_readlane_b32 s11, v217, 57
	v_readlane_b32 s12, v217, 58
	v_readlane_b32 s13, v217, 59
	v_readlane_b32 s14, v217, 60
	v_readlane_b32 s15, v217, 61
	v_readlane_b32 s16, v217, 62
	v_readlane_b32 s17, v217, 63
	v_readlane_b32 s18, v216, 0
	v_writelane_b32 v214, s1, 58
	s_mov_b32 s0, 0
	v_writelane_b32 v255, s0, 7
	s_branch .LBB0_117

.LBB0_117:
	s_waitcnt lgkmcnt(0)
	s_barrier
	v_readlane_b32 s0, v255, 7
	v_readlane_b32 s1, v217, 0
	s_and_b32 s6, s1, 7
	s_lshr_b32 s1, s1, 3
	s_add_u32 s7, s0, 1
	v_writelane_b32 v255, s7, 7
	s_cmp_lt_u32 s1, 16
	s_cbranch_scc0 .Lmx_small
	s_cmp_eq_u32 s0, 0
	s_cselect_b32 s9, s1, -1
	s_branch .Lmx_res
.Lmx_small:
	s_sub_u32 s1, s1, 16
	s_lshl_b32 s9, s1, 1
	s_add_u32 s9, s9, 16
	s_add_u32 s9, s9, s0
	s_add_u32 s10, s1, 48
	s_add_u32 s11, s1, 64
	s_cmp_lt_u32 s1, 8
	s_cselect_b32 s11, s11, -1
	s_cmp_eq_u32 s0, 2
	s_cselect_b32 s9, s10, s9
	s_cmp_eq_u32 s0, 3
	s_cselect_b32 s9, s11, s9
	s_cmp_gt_u32 s0, 3
	s_cselect_b32 s9, -1, s9
.Lmx_res:
	s_lshl_b32 s6, s6, 8
	s_add_u32 s6, s6, s9
	s_cmp_lt_i32 s9, 0
	s_cselect_b32 s6, -1, s6
	v_mov_b32_e32 v2, s6
	s_mov_b64 s[4:5], -1
	s_waitcnt lgkmcnt(0)
	v_cmp_lt_i32_e32 vcc, -1, v2
	s_and_saveexec_b64 s[0:1], vcc
	s_cbranch_execz .LBB0_116
	v_and_b32_e32 v0, 0xff, v2
	v_lshrrev_b32_e32 v3, 8, v2
	v_cmp_lt_u32_e32 vcc, 15, v0
	s_and_saveexec_b64 s[4:5], vcc
	s_xor_b64 s[40:41], exec, s[4:5]
	s_cbranch_execz .LBB0_152
	v_cmp_lt_u32_e32 vcc, 47, v0
	s_and_saveexec_b64 s[4:5], vcc
	s_xor_b64 s[4:5], exec, s[4:5]
	s_cbranch_execz .LBB0_137
	v_mad_u32_u24 v0, v3, 24, v0
	v_mov_b32_e32 v56, v142
	v_lshl_add_u32 v0, v0, 5, v155
	s_movk_i32 s6, 0x80
	v_and_b32_e32 v60, 0x7fffff80, v0
	v_cmp_gt_i32_e32 vcc, s6, v56
	s_barrier
	s_and_saveexec_b64 s[6:7], vcc
	s_cbranch_execz .LBB0_136
	v_add_u32_e32 v4, v56, v60
	v_ashrrev_i32_e32 v5, 31, v4
	v_readlane_b32 s8, v217, 35
	v_lshlrev_b64 v[4:5], 6, v[4:5]
	v_readlane_b32 s9, v217, 36
	v_lshl_add_u32 v3, v56, 2, 0
	v_add_u32_e32 v3, 0x24000, v3
	v_lshl_add_u64 v[16:17], s[8:9], 0, v[4:5]
	global_load_dwordx4 v[4:7], v[16:17], off
	global_load_dwordx4 v[8:11], v[16:17], off offset:16
	global_load_dwordx4 v[12:15], v[16:17], off offset:32
	s_nop 0
	global_load_dwordx4 v[16:19], v[16:17], off offset:48
	s_waitcnt vmcnt(2)
	v_pk_add_f32 v[4:5], v[4:5], v[8:9]
	v_pk_add_f32 v[6:7], v[6:7], v[10:11]
	s_waitcnt vmcnt(1)
	v_pk_add_f32 v[4:5], v[4:5], v[12:13]
	v_pk_add_f32 v[6:7], v[6:7], v[14:15]
	s_waitcnt vmcnt(0)
	v_pk_add_f32 v[4:5], v[4:5], v[16:17]
	v_pk_add_f32 v[6:7], v[6:7], v[18:19]
	v_add_f32_e32 v0, v4, v5
	v_add_f32_e32 v0, v6, v0
	v_add_f32_e32 v0, v7, v0
	v_fmamk_f32 v0, v0, 0x3a800000, v144
	v_rsq_f32_e32 v0, v0
	ds_write_b32 v3, v0
